# attention softmax: packed f32 fma (scale/offset) and packed row-sum adds; later code kept at the same 64-byte placement
# speedup vs baseline: 1.0125x; 1.0125x over previous
; #define LAS __attribute__((address_space(3)))
; __device__ __forceinline__ unsigned pk2(float lo, float hi) { const f32x2 v = {lo, hi}; return __builtin_bit_cast(unsigned, __builtin_convertvector(v, hwbf16x2)); }
; __device__ __forceinline__ void attn_tile(const LAS unsigned char* Kb, const LAS unsigned char* Vb, const LAS f32x4* bp, const bf16x8 (&qr)[4], f32x16 (&o)[2], float& m, float& l, int r32, int hi) {
;     ...
;     float ls = 0.f; const float nm = -m;
; #pragma unroll
;     for (int r = 0; r < 16; ++r) { p0[r] = __builtin_amdgcn_exp2f(p0[r] * C2 + nm); p1[r] = __builtin_amdgcn_exp2f(p1[r] * C2 + nm); ls += p0[r] + p1[r]; }
;     l += ls;
;     u32x4 pw[4];
; #pragma unroll
;     for (int s = 0; s < 2; ++s) {
;         pw[s] = (u32x4){pk2(p0[8 * s], p0[8 * s + 1]), pk2(p0[8 * s + 2], p0[8 * s + 3]), pk2(p0[8 * s + 4], p0[8 * s + 5]), pk2(p0[8 * s + 6], p0[8 * s + 7])};
;         pw[2 + s] = (u32x4){pk2(p1[8 * s], p1[8 * s + 1]), pk2(p1[8 * s + 2], p1[8 * s + 3]), pk2(p1[8 * s + 4], p1[8 * s + 5]), pk2(p1[8 * s + 6], p1[8 * s + 7])};
;     }
; #pragma unroll
;     for (int dh = 0; dh < 2; ++dh)
; #pragma unroll
;         for (int ks = 0; ks < 4; ++ks) {
;             const bf16x8 vf = *(const LAS bf16x8*)(Vb + (32 * dh + r32) * 144 + (16 * ks + 8 * hi) * 2);
;             o[dh] = __builtin_amdgcn_mfma_f32_32x32x16_bf16(vf, __builtin_bit_cast(bf16x8, pw[ks]), o[dh], 0, 0, 0);
;         }
.Latt_keep_a:
	v_mov_b32_e32 v158, s6
	v_pk_fma_f32 v[48:49], v[48:49], v[158:159], v[116:117] op_sel:[0,0,1] op_sel_hi:[1,0,1] neg_lo:[0,0,1] neg_hi:[0,0,1]
	v_pk_fma_f32 v[50:51], v[50:51], v[158:159], v[116:117] op_sel:[0,0,1] op_sel_hi:[1,0,1] neg_lo:[0,0,1] neg_hi:[0,0,1]
	v_pk_fma_f32 v[52:53], v[52:53], v[158:159], v[116:117] op_sel:[0,0,1] op_sel_hi:[1,0,1] neg_lo:[0,0,1] neg_hi:[0,0,1]
	v_pk_fma_f32 v[54:55], v[54:55], v[158:159], v[116:117] op_sel:[0,0,1] op_sel_hi:[1,0,1] neg_lo:[0,0,1] neg_hi:[0,0,1]
	v_exp_f32_e32 v48, v48
	v_exp_f32_e32 v49, v49
	v_exp_f32_e32 v50, v50
	v_exp_f32_e32 v51, v51
	v_exp_f32_e32 v52, v52
	v_exp_f32_e32 v53, v53
	v_exp_f32_e32 v54, v54
	v_exp_f32_e32 v55, v55
	v_pk_add_f32 v[130:131], v[48:49], v[50:51]
	v_pk_add_f32 v[130:131], v[130:131], v[52:53]
	v_pk_add_f32 v[130:131], v[130:131], v[54:55]
	v_cvt_pk_bf16_f32 v48, v48, v49
	v_cvt_pk_bf16_f32 v49, v50, v51
	v_cvt_pk_bf16_f32 v50, v52, v53
	v_cvt_pk_bf16_f32 v51, v54, v55
	v_pk_fma_f32 v[56:57], v[56:57], v[158:159], v[116:117] op_sel:[0,0,1] op_sel_hi:[1,0,1] neg_lo:[0,0,1] neg_hi:[0,0,1]
	v_pk_fma_f32 v[58:59], v[58:59], v[158:159], v[116:117] op_sel:[0,0,1] op_sel_hi:[1,0,1] neg_lo:[0,0,1] neg_hi:[0,0,1]
	v_pk_fma_f32 v[60:61], v[60:61], v[158:159], v[116:117] op_sel:[0,0,1] op_sel_hi:[1,0,1] neg_lo:[0,0,1] neg_hi:[0,0,1]
	v_pk_fma_f32 v[62:63], v[62:63], v[158:159], v[116:117] op_sel:[0,0,1] op_sel_hi:[1,0,1] neg_lo:[0,0,1] neg_hi:[0,0,1]
	v_exp_f32_e32 v56, v56
	v_exp_f32_e32 v57, v57
	v_exp_f32_e32 v58, v58
	v_exp_f32_e32 v59, v59
	v_exp_f32_e32 v60, v60
	v_exp_f32_e32 v61, v61
	v_exp_f32_e32 v62, v62
	v_exp_f32_e32 v63, v63
	v_mfma_f32_32x32x16_bf16 v[16:31], v[138:141], v[48:51], v[16:31]
	v_mfma_f32_32x32x16_bf16 v[0:15], v[154:157], v[48:51], v[0:15]
	v_pk_add_f32 v[130:131], v[130:131], v[56:57]
	v_pk_add_f32 v[130:131], v[130:131], v[58:59]
	v_pk_add_f32 v[130:131], v[130:131], v[60:61]
	v_pk_add_f32 v[130:131], v[130:131], v[62:63]
	v_cvt_pk_bf16_f32 v52, v56, v57
	v_cvt_pk_bf16_f32 v53, v58, v59
	v_cvt_pk_bf16_f32 v54, v60, v61
	v_cvt_pk_bf16_f32 v55, v62, v63
	v_pk_fma_f32 v[32:33], v[32:33], v[158:159], v[116:117] op_sel:[0,0,1] op_sel_hi:[1,0,1] neg_lo:[0,0,1] neg_hi:[0,0,1]
	v_pk_fma_f32 v[34:35], v[34:35], v[158:159], v[116:117] op_sel:[0,0,1] op_sel_hi:[1,0,1] neg_lo:[0,0,1] neg_hi:[0,0,1]
	v_pk_fma_f32 v[36:37], v[36:37], v[158:159], v[116:117] op_sel:[0,0,1] op_sel_hi:[1,0,1] neg_lo:[0,0,1] neg_hi:[0,0,1]
	v_pk_fma_f32 v[38:39], v[38:39], v[158:159], v[116:117] op_sel:[0,0,1] op_sel_hi:[1,0,1] neg_lo:[0,0,1] neg_hi:[0,0,1]
	v_exp_f32_e32 v32, v32
	v_exp_f32_e32 v33, v33
	v_exp_f32_e32 v34, v34
	v_exp_f32_e32 v35, v35
	v_exp_f32_e32 v36, v36
	v_exp_f32_e32 v37, v37
	v_exp_f32_e32 v38, v38
	v_exp_f32_e32 v39, v39
	v_mfma_f32_32x32x16_bf16 v[16:31], v[142:145], v[52:55], v[16:31]
	v_mfma_f32_32x32x16_bf16 v[0:15], v[118:121], v[52:55], v[0:15]
	v_pk_add_f32 v[130:131], v[130:131], v[32:33]
	v_pk_add_f32 v[130:131], v[130:131], v[34:35]
	v_pk_add_f32 v[130:131], v[130:131], v[36:37]
	v_pk_add_f32 v[130:131], v[130:131], v[38:39]
	v_cvt_pk_bf16_f32 v32, v32, v33
	v_cvt_pk_bf16_f32 v33, v34, v35
	v_cvt_pk_bf16_f32 v34, v36, v37
	v_cvt_pk_bf16_f32 v35, v38, v39
	v_pk_fma_f32 v[40:41], v[40:41], v[158:159], v[116:117] op_sel:[0,0,1] op_sel_hi:[1,0,1] neg_lo:[0,0,1] neg_hi:[0,0,1]
	v_pk_fma_f32 v[42:43], v[42:43], v[158:159], v[116:117] op_sel:[0,0,1] op_sel_hi:[1,0,1] neg_lo:[0,0,1] neg_hi:[0,0,1]
	v_pk_fma_f32 v[44:45], v[44:45], v[158:159], v[116:117] op_sel:[0,0,1] op_sel_hi:[1,0,1] neg_lo:[0,0,1] neg_hi:[0,0,1]
	v_pk_fma_f32 v[46:47], v[46:47], v[158:159], v[116:117] op_sel:[0,0,1] op_sel_hi:[1,0,1] neg_lo:[0,0,1] neg_hi:[0,0,1]
	v_exp_f32_e32 v40, v40
	v_exp_f32_e32 v41, v41
	v_exp_f32_e32 v42, v42
	v_exp_f32_e32 v43, v43
	v_exp_f32_e32 v44, v44
	v_exp_f32_e32 v45, v45
	v_exp_f32_e32 v46, v46
	v_exp_f32_e32 v47, v47
	v_mfma_f32_32x32x16_bf16 v[16:31], v[146:149], v[32:35], v[16:31]
	v_mfma_f32_32x32x16_bf16 v[0:15], v[122:125], v[32:35], v[0:15]
	v_pk_add_f32 v[130:131], v[130:131], v[40:41]
	v_pk_add_f32 v[130:131], v[130:131], v[42:43]
	v_pk_add_f32 v[130:131], v[130:131], v[44:45]
	v_pk_add_f32 v[130:131], v[130:131], v[46:47]
	v_cvt_pk_bf16_f32 v36, v40, v41
	v_cvt_pk_bf16_f32 v37, v42, v43
	v_cvt_pk_bf16_f32 v38, v44, v45
	v_cvt_pk_bf16_f32 v39, v46, v47
	v_add_f32_e32 v130, v130, v131
	v_add_f32_e32 v101, v101, v130
	v_mfma_f32_32x32x16_bf16 v[16:31], v[150:153], v[36:39], v[16:31]
	v_mfma_f32_32x32x16_bf16 v[0:15], v[126:129], v[36:39], v[0:15]

; #define LDS_BARRIER() asm volatile("s_waitcnt lgkmcnt(0)\n\ts_barrier" ::: "memory")
; #define AT_LOAD(K_, V_, kt) do { const bf16_t* s_ = kvsrc + (size_t)(kt) * 64 * NQKV; K_ = *(const bf16x8*)s_; V_ = *(const bf16x8*)(s_ + 1024); } while (0)
; #define AT_STORE(K_, V_, buf) do { *(LAS bf16x8*)(lds + AT_KOFF + (buf) * 9216 + srow * 144 + sch * 16) = K_; \
;         _Pragma("unroll") for (int j_ = 0; j_ < 8; ++j_) *(LAS short*)(lds + AT_VOFF + (buf) * 9216 + (8 * sch + j_) * 144 + vp * 2) = V_[j_]; } while (0)
; __device__ __forceinline__ void attn_prompt_unit(const Params& P, LAS unsigned char* lds, int li, int b, int h, int g4, const int tid) {
;     ...
;     for (int kt = kt_lo; kt <= kt_hi; kt += 2) {
;         if (kt + 2 <= kt_hi) AT_LOAD(kA, vA, kt + 2);
;         if (kt >= cw - 8 && kt <= cw) attn_tile(lds + AT_KOFF, lds + AT_VOFF, btl + min(cw - kt, 3) * 1024, qr, o, m, l, r32, hi);
;         AT_STORE(kB, vB, 1);
;         LDS_BARRIER();
;         if (kt + 3 <= kt_hi) AT_LOAD(kB, vB, kt + 3);
;         if (kt + 1 >= cw - 8 && kt + 1 <= cw) attn_tile(lds + AT_KOFF + 9216, lds + AT_VOFF + 9216, btl + min(cw - kt - 1, 3) * 1024, qr, o, m, l, r32, hi);
;         if (kt + 2 <= kt_hi) AT_STORE(kA, vA, 0);
;         LDS_BARRIER();
;     }
.LBB0_85:
	s_waitcnt lgkmcnt(0)
	s_barrier
	s_andn2_b64 vcc, exec, s[0:1]
	s_mov_b64 s[0:1], 0xc0000
	s_add_i32 s26, s26, -2
	v_lshl_add_u64 v[106:107], v[106:107], 0, s[0:1]
	s_cbranch_vccz .LBB0_68
	s_mov_b32 s28, s27
	s_branch .LBB0_71
	s_nop 0
	s_nop 0
	s_nop 0
	s_nop 0
	s_nop 0
	s_nop 0
	s_nop 0
	s_nop 0
	s_nop 0
	s_nop 0
	s_nop 0
	s_nop 0
	s_nop 0
	s_nop 0
